# stack18 plus: waiting workgroups issue their first release poll in front of the L1 invalidate instead of behind it
# baseline (speedup 1.0000x reference)
.LBB0_80:
	s_or_b64 exec, exec, s[12:13]
	v_cvt_f32_u32_e32 v5, v3
	s_waitcnt vmcnt(0)
	v_readfirstlane_b32 s10, v4
	s_add_u32 s8, s8, 0x2400
	s_addc_u32 s9, s9, 0
	v_add_u32_e32 v6, s10, v2
	v_add_u32_e32 v4, 1, v6
	v_mul_u32_u24_e32 v3, 1, v3
	v_mov_b32_e32 v2, 0
	v_cmp_ne_u32_e32 vcc, v4, v3
	s_and_saveexec_b64 s[10:11], vcc
	s_xor_b64 s[10:11], exec, s[10:11]
	s_cbranch_execz .LBB0_94
	s_waitcnt lgkmcnt(0)
	v_mov_b32_e32 v1, 0
	global_load_dword v3, v1, s[8:9] sc1
	buffer_inv sc1
	s_waitcnt vmcnt(0)
	v_cmp_eq_u32_e32 vcc, v3, v2
	s_and_saveexec_b64 s[12:13], vcc
	s_cbranch_execz .LBB0_93
	s_mov_b32 s24, 1
	s_mov_b64 s[14:15], 0
	s_branch .LBB0_84

.LBB0_174:
	s_or_b64 exec, exec, s[12:13]
	v_cvt_f32_u32_e32 v5, v3
	s_waitcnt vmcnt(0)
	v_readfirstlane_b32 s10, v4
	s_add_u32 s8, s8, 0x2400
	s_addc_u32 s9, s9, 0
	v_add_u32_e32 v6, s10, v2
	v_add_u32_e32 v4, 1, v6
	v_mul_u32_u24_e32 v3, 2, v3
	v_mov_b32_e32 v2, 1
	v_cmp_ne_u32_e32 vcc, v4, v3
	s_and_saveexec_b64 s[10:11], vcc
	s_xor_b64 s[10:11], exec, s[10:11]
	s_cbranch_execz .LBB0_188
	s_waitcnt lgkmcnt(0)
	v_mov_b32_e32 v1, 0
	global_load_dword v3, v1, s[8:9] sc1
	buffer_inv sc1
	s_waitcnt vmcnt(0)
	v_cmp_eq_u32_e32 vcc, v3, v2
	s_and_saveexec_b64 s[12:13], vcc
	s_cbranch_execz .LBB0_187
	s_mov_b32 s24, 1
	s_mov_b64 s[14:15], 0
	s_branch .LBB0_178

.LBB0_271:
	s_or_b64 exec, exec, s[12:13]
	v_cvt_f32_u32_e32 v5, v3
	s_waitcnt vmcnt(0)
	v_readfirstlane_b32 s10, v4
	s_add_u32 s8, s8, 0x2400
	s_addc_u32 s9, s9, 0
	v_add_u32_e32 v6, s10, v2
	v_add_u32_e32 v4, 1, v6
	v_mul_u32_u24_e32 v3, 3, v3
	v_mov_b32_e32 v2, 2
	v_cmp_ne_u32_e32 vcc, v4, v3
	s_and_saveexec_b64 s[10:11], vcc
	s_xor_b64 s[10:11], exec, s[10:11]
	s_cbranch_execz .LBB0_285
	s_waitcnt lgkmcnt(0)
	v_mov_b32_e32 v1, 0
	global_load_dword v3, v1, s[8:9] sc1
	buffer_inv sc1
	s_waitcnt vmcnt(0)
	v_cmp_eq_u32_e32 vcc, v3, v2
	s_and_saveexec_b64 s[12:13], vcc
	s_cbranch_execz .LBB0_284
	s_mov_b32 s24, 1
	s_mov_b64 s[14:15], 0
	s_branch .LBB0_275

.LBB0_343:
	s_or_b64 exec, exec, s[12:13]
	v_cvt_f32_u32_e32 v5, v3
	s_waitcnt vmcnt(0)
	v_readfirstlane_b32 s10, v4
	s_add_u32 s8, s8, 0x2400
	s_addc_u32 s9, s9, 0
	v_add_u32_e32 v6, s10, v2
	v_add_u32_e32 v4, 1, v6
	v_mul_u32_u24_e32 v3, 4, v3
	v_mov_b32_e32 v2, 3
	v_cmp_ne_u32_e32 vcc, v4, v3
	s_and_saveexec_b64 s[10:11], vcc
	s_xor_b64 s[10:11], exec, s[10:11]
	s_cbranch_execz .LBB0_357
	s_waitcnt lgkmcnt(0)
	v_mov_b32_e32 v1, 0
	global_load_dword v3, v1, s[8:9] sc1
	buffer_inv sc1
	s_waitcnt vmcnt(0)
	v_cmp_eq_u32_e32 vcc, v3, v2
	s_and_saveexec_b64 s[12:13], vcc
	s_cbranch_execz .LBB0_356
	s_mov_b32 s24, 1
	s_mov_b64 s[14:15], 0
	s_branch .LBB0_347

.LBB0_442:
	s_or_b64 exec, exec, s[12:13]
	v_cvt_f32_u32_e32 v5, v3
	s_waitcnt vmcnt(0)
	v_readfirstlane_b32 s10, v4
	s_add_u32 s8, s8, 0x2400
	s_addc_u32 s9, s9, 0
	v_add_u32_e32 v6, s10, v2
	v_add_u32_e32 v4, 1, v6
	v_mul_u32_u24_e32 v3, 5, v3
	v_mov_b32_e32 v2, 4
	v_cmp_ne_u32_e32 vcc, v4, v3
	s_and_saveexec_b64 s[10:11], vcc
	s_xor_b64 s[10:11], exec, s[10:11]
	s_cbranch_execz .LBB0_456
	s_waitcnt lgkmcnt(0)
	v_mov_b32_e32 v1, 0
	global_load_dword v3, v1, s[8:9] sc1
	buffer_inv sc1
	s_waitcnt vmcnt(0)
	v_cmp_eq_u32_e32 vcc, v3, v2
	s_and_saveexec_b64 s[12:13], vcc
	s_cbranch_execz .LBB0_455
	s_mov_b32 s24, 1
	s_mov_b64 s[14:15], 0
	s_branch .LBB0_446

.LBB0_519:
	s_or_b64 exec, exec, s[12:13]
	v_cvt_f32_u32_e32 v5, v3
	s_waitcnt vmcnt(0)
	v_readfirstlane_b32 s10, v4
	s_add_u32 s8, s8, 0x2400
	s_addc_u32 s9, s9, 0
	v_add_u32_e32 v6, s10, v2
	v_add_u32_e32 v4, 1, v6
	v_mul_u32_u24_e32 v3, 6, v3
	v_mov_b32_e32 v2, 5
	v_cmp_ne_u32_e32 vcc, v4, v3
	s_and_saveexec_b64 s[10:11], vcc
	s_xor_b64 s[10:11], exec, s[10:11]
	s_cbranch_execz .LBB0_533
	s_waitcnt lgkmcnt(0)
	v_mov_b32_e32 v1, 0
	global_load_dword v3, v1, s[8:9] sc1
	buffer_inv sc1
	s_waitcnt vmcnt(0)
	v_cmp_eq_u32_e32 vcc, v3, v2
	s_and_saveexec_b64 s[12:13], vcc
	s_cbranch_execz .LBB0_532
	s_mov_b32 s24, 1
	s_mov_b64 s[14:15], 0
	s_branch .LBB0_523

.LBB0_600:
	s_or_b64 exec, exec, s[12:13]
	v_cvt_f32_u32_e32 v5, v3
	s_waitcnt vmcnt(0)
	v_readfirstlane_b32 s10, v4
	s_add_u32 s8, s8, 0x2400
	s_addc_u32 s9, s9, 0
	v_add_u32_e32 v6, s10, v2
	v_add_u32_e32 v4, 1, v6
	v_mul_u32_u24_e32 v3, 7, v3
	v_mov_b32_e32 v2, 6
	v_cmp_ne_u32_e32 vcc, v4, v3
	s_and_saveexec_b64 s[10:11], vcc
	s_xor_b64 s[10:11], exec, s[10:11]
	s_cbranch_execz .LBB0_614
	s_waitcnt lgkmcnt(0)
	v_mov_b32_e32 v1, 0
	global_load_dword v3, v1, s[8:9] sc1
	buffer_inv sc1
	s_waitcnt vmcnt(0)
	v_cmp_eq_u32_e32 vcc, v3, v2
	s_and_saveexec_b64 s[12:13], vcc
	s_cbranch_execz .LBB0_613
	s_mov_b32 s24, 1
	s_mov_b64 s[14:15], 0
	s_branch .LBB0_604

.LBB0_680:
	s_or_b64 exec, exec, s[12:13]
	v_cvt_f32_u32_e32 v5, v3
	s_waitcnt vmcnt(0)
	v_readfirstlane_b32 s10, v4
	s_add_u32 s8, s8, 0x2400
	s_addc_u32 s9, s9, 0
	v_add_u32_e32 v6, s10, v2
	v_add_u32_e32 v4, 1, v6
	v_mul_u32_u24_e32 v3, 8, v3
	v_mov_b32_e32 v2, 7
	v_cmp_ne_u32_e32 vcc, v4, v3
	s_and_saveexec_b64 s[10:11], vcc
	s_xor_b64 s[10:11], exec, s[10:11]
	s_cbranch_execz .LBB0_694
	s_waitcnt lgkmcnt(0)
	v_mov_b32_e32 v1, 0
	global_load_dword v3, v1, s[8:9] sc1
	buffer_inv sc1
	s_waitcnt vmcnt(0)
	v_cmp_eq_u32_e32 vcc, v3, v2
	s_and_saveexec_b64 s[12:13], vcc
	s_cbranch_execz .LBB0_693
	s_mov_b32 s24, 1
	s_mov_b64 s[14:15], 0
	s_branch .LBB0_684

.LBB0_774:
	s_or_b64 exec, exec, s[12:13]
	v_cvt_f32_u32_e32 v5, v3
	s_waitcnt vmcnt(0)
	v_readfirstlane_b32 s10, v4
	s_add_u32 s8, s8, 0x2400
	s_addc_u32 s9, s9, 0
	v_add_u32_e32 v6, s10, v2
	v_add_u32_e32 v4, 1, v6
	v_mul_u32_u24_e32 v3, 9, v3
	v_mov_b32_e32 v2, 8
	v_cmp_ne_u32_e32 vcc, v4, v3
	s_and_saveexec_b64 s[10:11], vcc
	s_xor_b64 s[10:11], exec, s[10:11]
	s_cbranch_execz .LBB0_788
	s_waitcnt lgkmcnt(0)
	v_mov_b32_e32 v1, 0
	global_load_dword v3, v1, s[8:9] sc1
	buffer_inv sc1
	s_waitcnt vmcnt(0)
	v_cmp_eq_u32_e32 vcc, v3, v2
	s_and_saveexec_b64 s[12:13], vcc
	s_cbranch_execz .LBB0_787
	s_mov_b32 s24, 1
	s_mov_b64 s[14:15], 0
	s_branch .LBB0_778

.LBB0_871:
	s_or_b64 exec, exec, s[12:13]
	v_cvt_f32_u32_e32 v5, v3
	s_waitcnt vmcnt(0)
	v_readfirstlane_b32 s10, v4
	s_add_u32 s8, s8, 0x2400
	s_addc_u32 s9, s9, 0
	v_add_u32_e32 v6, s10, v2
	v_add_u32_e32 v4, 1, v6
	v_mul_u32_u24_e32 v3, 10, v3
	v_mov_b32_e32 v2, 9
	v_cmp_ne_u32_e32 vcc, v4, v3
	s_and_saveexec_b64 s[10:11], vcc
	s_xor_b64 s[10:11], exec, s[10:11]
	s_cbranch_execz .LBB0_885
	s_waitcnt lgkmcnt(0)
	v_mov_b32_e32 v1, 0
	global_load_dword v3, v1, s[8:9] sc1
	buffer_inv sc1
	s_waitcnt vmcnt(0)
	v_cmp_eq_u32_e32 vcc, v3, v2
	s_and_saveexec_b64 s[12:13], vcc
	s_cbranch_execz .LBB0_884
	s_mov_b32 s24, 1
	s_mov_b64 s[14:15], 0
	s_branch .LBB0_875

.LBB0_951:
	s_or_b64 exec, exec, s[12:13]
	v_cvt_f32_u32_e32 v5, v3
	s_waitcnt vmcnt(0)
	v_readfirstlane_b32 s10, v4
	s_add_u32 s8, s8, 0x2400
	s_addc_u32 s9, s9, 0
	v_add_u32_e32 v6, s10, v2
	v_add_u32_e32 v4, 1, v6
	v_mul_u32_u24_e32 v3, 11, v3
	v_mov_b32_e32 v2, 10
	v_cmp_ne_u32_e32 vcc, v4, v3
	s_and_saveexec_b64 s[10:11], vcc
	s_xor_b64 s[10:11], exec, s[10:11]
	s_cbranch_execz .LBB0_965
	s_waitcnt lgkmcnt(0)
	v_mov_b32_e32 v1, 0
	global_load_dword v3, v1, s[8:9] sc1
	buffer_inv sc1
	s_waitcnt vmcnt(0)
	v_cmp_eq_u32_e32 vcc, v3, v2
	s_and_saveexec_b64 s[12:13], vcc
	s_cbranch_execz .LBB0_964
	s_mov_b32 s24, 1
	s_mov_b64 s[14:15], 0
	s_branch .LBB0_955

.LBB0_1045:
	s_or_b64 exec, exec, s[12:13]
	v_cvt_f32_u32_e32 v5, v3
	s_waitcnt vmcnt(0)
	v_readfirstlane_b32 s10, v4
	s_add_u32 s8, s8, 0x2400
	s_addc_u32 s9, s9, 0
	v_add_u32_e32 v6, s10, v2
	v_add_u32_e32 v4, 1, v6
	v_mul_u32_u24_e32 v3, 12, v3
	v_mov_b32_e32 v2, 11
	v_cmp_ne_u32_e32 vcc, v4, v3
	s_and_saveexec_b64 s[10:11], vcc
	s_xor_b64 s[10:11], exec, s[10:11]
	s_cbranch_execz .LBB0_1059
	s_waitcnt lgkmcnt(0)
	v_mov_b32_e32 v1, 0
	global_load_dword v3, v1, s[8:9] sc1
	buffer_inv sc1
	s_waitcnt vmcnt(0)
	v_cmp_eq_u32_e32 vcc, v3, v2
	s_and_saveexec_b64 s[12:13], vcc
	s_cbranch_execz .LBB0_1058
	s_mov_b32 s24, 1
	s_mov_b64 s[14:15], 0
	s_branch .LBB0_1049

.LBB0_1142:
	s_or_b64 exec, exec, s[12:13]
	v_cvt_f32_u32_e32 v5, v3
	s_waitcnt vmcnt(0)
	v_readfirstlane_b32 s10, v4
	s_add_u32 s8, s8, 0x2400
	s_addc_u32 s9, s9, 0
	v_add_u32_e32 v6, s10, v2
	v_add_u32_e32 v4, 1, v6
	v_mul_u32_u24_e32 v3, 13, v3
	v_mov_b32_e32 v2, 12
	v_cmp_ne_u32_e32 vcc, v4, v3
	s_and_saveexec_b64 s[10:11], vcc
	s_xor_b64 s[10:11], exec, s[10:11]
	s_cbranch_execz .LBB0_1156
	s_waitcnt lgkmcnt(0)
	v_mov_b32_e32 v1, 0
	global_load_dword v3, v1, s[8:9] sc1
	buffer_inv sc1
	s_waitcnt vmcnt(0)
	v_cmp_eq_u32_e32 vcc, v3, v2
	s_and_saveexec_b64 s[12:13], vcc
	s_cbranch_execz .LBB0_1155
	s_mov_b32 s24, 1
	s_mov_b64 s[14:15], 0
	s_branch .LBB0_1146

.LBB0_1214:
	s_or_b64 exec, exec, s[12:13]
	v_cvt_f32_u32_e32 v5, v3
	s_waitcnt vmcnt(0)
	v_readfirstlane_b32 s10, v4
	s_add_u32 s8, s8, 0x2400
	s_addc_u32 s9, s9, 0
	v_add_u32_e32 v6, s10, v2
	v_add_u32_e32 v4, 1, v6
	v_mul_u32_u24_e32 v3, 14, v3
	v_mov_b32_e32 v2, 13
	v_cmp_ne_u32_e32 vcc, v4, v3
	s_and_saveexec_b64 s[10:11], vcc
	s_xor_b64 s[10:11], exec, s[10:11]
	s_cbranch_execz .LBB0_1228
	s_waitcnt lgkmcnt(0)
	v_mov_b32_e32 v1, 0
	global_load_dword v3, v1, s[8:9] sc1
	buffer_inv sc1
	s_waitcnt vmcnt(0)
	v_cmp_eq_u32_e32 vcc, v3, v2
	s_and_saveexec_b64 s[12:13], vcc
	s_cbranch_execz .LBB0_1227
	s_mov_b32 s24, 1
	s_mov_b64 s[14:15], 0
	s_branch .LBB0_1218

.LBB0_1291:
	s_or_b64 exec, exec, s[12:13]
	v_cvt_f32_u32_e32 v5, v3
	s_waitcnt vmcnt(0)
	v_readfirstlane_b32 s10, v4
	s_add_u32 s8, s8, 0x2400
	s_addc_u32 s9, s9, 0
	v_add_u32_e32 v6, s10, v2
	v_add_u32_e32 v4, 1, v6
	v_mul_u32_u24_e32 v3, 15, v3
	v_mov_b32_e32 v2, 14
	v_cmp_ne_u32_e32 vcc, v4, v3
	s_and_saveexec_b64 s[10:11], vcc
	s_xor_b64 s[10:11], exec, s[10:11]
	s_cbranch_execz .LBB0_1305
	s_waitcnt lgkmcnt(0)
	v_mov_b32_e32 v1, 0
	global_load_dword v3, v1, s[8:9] sc1
	buffer_inv sc1
	s_waitcnt vmcnt(0)
	v_cmp_eq_u32_e32 vcc, v3, v2
	s_and_saveexec_b64 s[12:13], vcc
	s_cbranch_execz .LBB0_1304
	s_mov_b32 s24, 1
	s_mov_b64 s[14:15], 0
	s_branch .LBB0_1295

.LBB0_1377:
	s_or_b64 exec, exec, s[12:13]
	v_cvt_f32_u32_e32 v5, v3
	s_waitcnt vmcnt(0)
	v_readfirstlane_b32 s10, v4
	s_add_u32 s8, s8, 0x2400
	s_addc_u32 s9, s9, 0
	v_add_u32_e32 v6, s10, v2
	v_add_u32_e32 v4, 1, v6
	v_mul_u32_u24_e32 v3, 16, v3
	v_mov_b32_e32 v2, 15
	v_cmp_ne_u32_e32 vcc, v4, v3
	s_and_saveexec_b64 s[10:11], vcc
	s_xor_b64 s[10:11], exec, s[10:11]
	s_cbranch_execz .LBB0_1391
	s_waitcnt lgkmcnt(0)
	v_mov_b32_e32 v1, 0
	global_load_dword v3, v1, s[8:9] sc1
	buffer_inv sc1
	s_waitcnt vmcnt(0)
	v_cmp_eq_u32_e32 vcc, v3, v2
	s_and_saveexec_b64 s[12:13], vcc
	s_cbranch_execz .LBB0_1390
	s_mov_b32 s26, 1
	s_mov_b64 s[14:15], 0
	s_branch .LBB0_1381

.LBB0_1458:
	s_or_b64 exec, exec, s[12:13]
	v_cvt_f32_u32_e32 v5, v3
	s_waitcnt vmcnt(0)
	v_readfirstlane_b32 s10, v4
	s_add_u32 s8, s8, 0x2400
	s_addc_u32 s9, s9, 0
	v_add_u32_e32 v6, s10, v2
	v_add_u32_e32 v4, 1, v6
	v_mul_u32_u24_e32 v3, 17, v3
	v_mov_b32_e32 v2, 16
	v_cmp_ne_u32_e32 vcc, v4, v3
	s_and_saveexec_b64 s[10:11], vcc
	s_xor_b64 s[10:11], exec, s[10:11]
	s_cbranch_execz .LBB0_1472
	s_waitcnt lgkmcnt(0)
	v_mov_b32_e32 v1, 0
	global_load_dword v3, v1, s[8:9] sc1
	buffer_inv sc1
	s_waitcnt vmcnt(0)
	v_cmp_eq_u32_e32 vcc, v3, v2
	s_and_saveexec_b64 s[12:13], vcc
	s_cbranch_execz .LBB0_1471
	s_mov_b32 s26, 1
	s_mov_b64 s[14:15], 0
	s_branch .LBB0_1462

.LBB0_1538:
	s_or_b64 exec, exec, s[12:13]
	v_cvt_f32_u32_e32 v5, v3
	s_waitcnt vmcnt(0)
	v_readfirstlane_b32 s10, v4
	s_add_u32 s8, s8, 0x2400
	s_addc_u32 s9, s9, 0
	v_add_u32_e32 v6, s10, v2
	v_add_u32_e32 v4, 1, v6
	v_mul_u32_u24_e32 v3, 18, v3
	v_mov_b32_e32 v2, 17
	v_cmp_ne_u32_e32 vcc, v4, v3
	s_and_saveexec_b64 s[10:11], vcc
	s_xor_b64 s[10:11], exec, s[10:11]
	s_cbranch_execz .LBB0_1552
	s_waitcnt lgkmcnt(0)
	v_mov_b32_e32 v1, 0
	global_load_dword v3, v1, s[8:9] sc1
	buffer_inv sc1
	s_waitcnt vmcnt(0)
	v_cmp_eq_u32_e32 vcc, v3, v2
	s_and_saveexec_b64 s[12:13], vcc
	s_cbranch_execz .LBB0_1551
	s_mov_b32 s26, 1
	s_mov_b64 s[14:15], 0
	s_branch .LBB0_1542

.LBB0_1632:
	s_or_b64 exec, exec, s[12:13]
	v_cvt_f32_u32_e32 v5, v3
	s_waitcnt vmcnt(0)
	v_readfirstlane_b32 s10, v4
	s_add_u32 s8, s8, 0x2400
	s_addc_u32 s9, s9, 0
	v_add_u32_e32 v6, s10, v2
	v_add_u32_e32 v4, 1, v6
	v_mul_u32_u24_e32 v3, 19, v3
	v_mov_b32_e32 v2, 18
	v_cmp_ne_u32_e32 vcc, v4, v3
	s_and_saveexec_b64 s[10:11], vcc
	s_xor_b64 s[10:11], exec, s[10:11]
	s_cbranch_execz .LBB0_1646
	s_waitcnt lgkmcnt(0)
	v_mov_b32_e32 v1, 0
	global_load_dword v3, v1, s[8:9] sc1
	buffer_inv sc1
	s_waitcnt vmcnt(0)
	v_cmp_eq_u32_e32 vcc, v3, v2
	s_and_saveexec_b64 s[12:13], vcc
	s_cbranch_execz .LBB0_1645
	s_mov_b32 s26, 1
	s_mov_b64 s[14:15], 0
	s_branch .LBB0_1636

.LBB0_1729:
	s_or_b64 exec, exec, s[12:13]
	v_cvt_f32_u32_e32 v5, v3
	s_waitcnt vmcnt(0)
	v_readfirstlane_b32 s10, v4
	s_add_u32 s8, s8, 0x2400
	s_addc_u32 s9, s9, 0
	v_add_u32_e32 v6, s10, v2
	v_add_u32_e32 v4, 1, v6
	v_mul_u32_u24_e32 v3, 20, v3
	v_mov_b32_e32 v2, 19
	v_cmp_ne_u32_e32 vcc, v4, v3
	s_and_saveexec_b64 s[10:11], vcc
	s_xor_b64 s[10:11], exec, s[10:11]
	s_cbranch_execz .LBB0_1743
	s_waitcnt lgkmcnt(0)
	v_mov_b32_e32 v1, 0
	global_load_dword v3, v1, s[8:9] sc1
	buffer_inv sc1
	s_waitcnt vmcnt(0)
	v_cmp_eq_u32_e32 vcc, v3, v2
	s_and_saveexec_b64 s[12:13], vcc
	s_cbranch_execz .LBB0_1742
	s_mov_b32 s26, 1
	s_mov_b64 s[14:15], 0
	s_branch .LBB0_1733

.LBB0_1809:
	s_or_b64 exec, exec, s[12:13]
	v_cvt_f32_u32_e32 v5, v3
	s_waitcnt vmcnt(0)
	v_readfirstlane_b32 s10, v4
	s_add_u32 s8, s8, 0x2400
	s_addc_u32 s9, s9, 0
	v_add_u32_e32 v6, s10, v2
	v_add_u32_e32 v4, 1, v6
	v_mul_u32_u24_e32 v3, 21, v3
	v_mov_b32_e32 v2, 20
	v_cmp_ne_u32_e32 vcc, v4, v3
	s_and_saveexec_b64 s[10:11], vcc
	s_xor_b64 s[10:11], exec, s[10:11]
	s_cbranch_execz .LBB0_1823
	s_waitcnt lgkmcnt(0)
	v_mov_b32_e32 v1, 0
	global_load_dword v3, v1, s[8:9] sc1
	buffer_inv sc1
	s_waitcnt vmcnt(0)
	v_cmp_eq_u32_e32 vcc, v3, v2
	s_and_saveexec_b64 s[12:13], vcc
	s_cbranch_execz .LBB0_1822
	s_mov_b32 s26, 1
	s_mov_b64 s[14:15], 0
	s_branch .LBB0_1813

.LBB0_1903:
	s_or_b64 exec, exec, s[12:13]
	v_cvt_f32_u32_e32 v5, v3
	s_waitcnt vmcnt(0)
	v_readfirstlane_b32 s10, v4
	s_add_u32 s8, s8, 0x2400
	s_addc_u32 s9, s9, 0
	v_add_u32_e32 v6, s10, v2
	v_add_u32_e32 v4, 1, v6
	v_mul_u32_u24_e32 v3, 22, v3
	v_mov_b32_e32 v2, 21
	v_cmp_ne_u32_e32 vcc, v4, v3
	s_and_saveexec_b64 s[10:11], vcc
	s_xor_b64 s[10:11], exec, s[10:11]
	s_cbranch_execz .LBB0_1917
	s_waitcnt lgkmcnt(0)
	v_mov_b32_e32 v1, 0
	global_load_dword v3, v1, s[8:9] sc1
	buffer_inv sc1
	s_waitcnt vmcnt(0)
	v_cmp_eq_u32_e32 vcc, v3, v2
	s_and_saveexec_b64 s[12:13], vcc
	s_cbranch_execz .LBB0_1916
	s_mov_b32 s26, 1
	s_mov_b64 s[14:15], 0
	s_branch .LBB0_1907

.LBB0_2000:
	s_or_b64 exec, exec, s[12:13]
	v_cvt_f32_u32_e32 v5, v3
	s_waitcnt vmcnt(0)
	v_readfirstlane_b32 s10, v4
	s_add_u32 s8, s8, 0x2400
	s_addc_u32 s9, s9, 0
	v_add_u32_e32 v6, s10, v2
	v_add_u32_e32 v4, 1, v6
	v_mul_u32_u24_e32 v3, 23, v3
	v_mov_b32_e32 v2, 22
	v_cmp_ne_u32_e32 vcc, v4, v3
	s_and_saveexec_b64 s[10:11], vcc
	s_xor_b64 s[10:11], exec, s[10:11]
	s_cbranch_execz .LBB0_2014
	s_waitcnt lgkmcnt(0)
	v_mov_b32_e32 v1, 0
	global_load_dword v3, v1, s[8:9] sc1
	buffer_inv sc1
	s_waitcnt vmcnt(0)
	v_cmp_eq_u32_e32 vcc, v3, v2
	s_and_saveexec_b64 s[12:13], vcc
	s_cbranch_execz .LBB0_2013
	s_mov_b32 s26, 1
	s_mov_b64 s[14:15], 0
	s_branch .LBB0_2004

.LBB0_2072:
	s_or_b64 exec, exec, s[12:13]
	v_cvt_f32_u32_e32 v5, v3
	s_waitcnt vmcnt(0)
	v_readfirstlane_b32 s10, v4
	s_add_u32 s8, s8, 0x2400
	s_addc_u32 s9, s9, 0
	v_add_u32_e32 v6, s10, v2
	v_add_u32_e32 v4, 1, v6
	v_mul_u32_u24_e32 v3, 24, v3
	v_mov_b32_e32 v2, 23
	v_cmp_ne_u32_e32 vcc, v4, v3
	s_and_saveexec_b64 s[10:11], vcc
	s_xor_b64 s[10:11], exec, s[10:11]
	s_cbranch_execz .LBB0_2086
	s_waitcnt lgkmcnt(0)
	v_mov_b32_e32 v1, 0
	global_load_dword v3, v1, s[8:9] sc1
	buffer_inv sc1
	s_waitcnt vmcnt(0)
	v_cmp_eq_u32_e32 vcc, v3, v2
	s_and_saveexec_b64 s[12:13], vcc
	s_cbranch_execz .LBB0_2085
	s_mov_b32 s26, 1
	s_mov_b64 s[14:15], 0
	s_branch .LBB0_2076

.LBB0_2252:
	s_or_b64 exec, exec, s[10:11]
	v_cvt_f32_u32_e32 v5, v3
	s_waitcnt vmcnt(0)
	v_readfirstlane_b32 s8, v4
	s_add_u32 s6, s6, 0x2400
	s_addc_u32 s7, s7, 0
	v_add_u32_e32 v6, s8, v2
	v_add_u32_e32 v4, 1, v6
	v_mul_u32_u24_e32 v3, 25, v3
	v_mov_b32_e32 v2, 24
	v_cmp_ne_u32_e32 vcc, v4, v3
	s_and_saveexec_b64 s[8:9], vcc
	s_xor_b64 s[8:9], exec, s[8:9]
	s_cbranch_execz .LBB0_2266
	s_waitcnt lgkmcnt(0)
	v_mov_b32_e32 v1, 0
	global_load_dword v3, v1, s[6:7] sc1
	buffer_inv sc1
	s_waitcnt vmcnt(0)
	v_cmp_eq_u32_e32 vcc, v3, v2
	s_and_saveexec_b64 s[10:11], vcc
	s_cbranch_execz .LBB0_2265
	s_mov_b32 s24, 1
	s_mov_b64 s[12:13], 0
	s_branch .LBB0_2256

.LBB0_2333:
	s_or_b64 exec, exec, s[10:11]
	v_cvt_f32_u32_e32 v5, v3
	s_waitcnt vmcnt(0)
	v_readfirstlane_b32 s8, v4
	s_add_u32 s6, s6, 0x2400
	s_addc_u32 s7, s7, 0
	v_add_u32_e32 v6, s8, v2
	v_add_u32_e32 v4, 1, v6
	v_mul_u32_u24_e32 v3, 26, v3
	v_mov_b32_e32 v2, 25
	v_cmp_ne_u32_e32 vcc, v4, v3
	s_and_saveexec_b64 s[8:9], vcc
	s_xor_b64 s[8:9], exec, s[8:9]
	s_cbranch_execz .LBB0_2347
	s_waitcnt lgkmcnt(0)
	v_mov_b32_e32 v1, 0
	global_load_dword v3, v1, s[6:7] sc1
	buffer_inv sc1
	s_waitcnt vmcnt(0)
	v_cmp_eq_u32_e32 vcc, v3, v2
	s_and_saveexec_b64 s[10:11], vcc
	s_cbranch_execz .LBB0_2346
	s_mov_b32 s24, 1
	s_mov_b64 s[12:13], 0
	s_branch .LBB0_2337

.LBB0_2413:
	s_or_b64 exec, exec, s[10:11]
	v_cvt_f32_u32_e32 v5, v3
	s_waitcnt vmcnt(0)
	v_readfirstlane_b32 s8, v4
	s_add_u32 s6, s6, 0x2400
	s_addc_u32 s7, s7, 0
	v_add_u32_e32 v6, s8, v2
	v_add_u32_e32 v4, 1, v6
	v_mul_u32_u24_e32 v3, 27, v3
	v_mov_b32_e32 v2, 26
	v_cmp_ne_u32_e32 vcc, v4, v3
	s_and_saveexec_b64 s[8:9], vcc
	s_xor_b64 s[8:9], exec, s[8:9]
	s_cbranch_execz .LBB0_2427
	s_waitcnt lgkmcnt(0)
	v_mov_b32_e32 v1, 0
	global_load_dword v3, v1, s[6:7] sc1
	buffer_inv sc1
	s_waitcnt vmcnt(0)
	v_cmp_eq_u32_e32 vcc, v3, v2
	s_and_saveexec_b64 s[10:11], vcc
	s_cbranch_execz .LBB0_2426
	s_mov_b32 s24, 1
	s_mov_b64 s[12:13], 0
	s_branch .LBB0_2417

.LBB0_2507:
	s_or_b64 exec, exec, s[10:11]
	v_cvt_f32_u32_e32 v5, v3
	s_waitcnt vmcnt(0)
	v_readfirstlane_b32 s8, v4
	s_add_u32 s6, s6, 0x2400
	s_addc_u32 s7, s7, 0
	v_add_u32_e32 v6, s8, v2
	v_add_u32_e32 v4, 1, v6
	v_mul_u32_u24_e32 v3, 28, v3
	v_mov_b32_e32 v2, 27
	v_cmp_ne_u32_e32 vcc, v4, v3
	s_and_saveexec_b64 s[8:9], vcc
	s_xor_b64 s[8:9], exec, s[8:9]
	s_cbranch_execz .LBB0_2521
	s_waitcnt lgkmcnt(0)
	v_mov_b32_e32 v1, 0
	global_load_dword v3, v1, s[6:7] sc1
	buffer_inv sc1
	s_waitcnt vmcnt(0)
	v_cmp_eq_u32_e32 vcc, v3, v2
	s_and_saveexec_b64 s[10:11], vcc
	s_cbranch_execz .LBB0_2520
	s_mov_b32 s24, 1
	s_mov_b64 s[12:13], 0
	s_branch .LBB0_2511

.LBB0_2604:
	s_or_b64 exec, exec, s[10:11]
	v_cvt_f32_u32_e32 v5, v3
	s_waitcnt vmcnt(0)
	v_readfirstlane_b32 s8, v4
	s_add_u32 s6, s6, 0x2400
	s_addc_u32 s7, s7, 0
	v_add_u32_e32 v6, s8, v2
	v_add_u32_e32 v4, 1, v6
	v_mul_u32_u24_e32 v3, 29, v3
	v_mov_b32_e32 v2, 28
	v_cmp_ne_u32_e32 vcc, v4, v3
	s_and_saveexec_b64 s[8:9], vcc
	s_xor_b64 s[8:9], exec, s[8:9]
	s_cbranch_execz .LBB0_2618
	s_waitcnt lgkmcnt(0)
	v_mov_b32_e32 v1, 0
	global_load_dword v3, v1, s[6:7] sc1
	buffer_inv sc1
	s_waitcnt vmcnt(0)
	v_cmp_eq_u32_e32 vcc, v3, v2
	s_and_saveexec_b64 s[10:11], vcc
	s_cbranch_execz .LBB0_2617
	s_mov_b32 s24, 1
	s_mov_b64 s[12:13], 0
	s_branch .LBB0_2608

.LBB0_2684:
	s_or_b64 exec, exec, s[10:11]
	v_cvt_f32_u32_e32 v5, v3
	s_waitcnt vmcnt(0)
	v_readfirstlane_b32 s8, v4
	s_add_u32 s6, s6, 0x2400
	s_addc_u32 s7, s7, 0
	v_add_u32_e32 v6, s8, v2
	v_add_u32_e32 v4, 1, v6
	v_mul_u32_u24_e32 v3, 30, v3
	v_mov_b32_e32 v2, 29
	v_cmp_ne_u32_e32 vcc, v4, v3
	s_and_saveexec_b64 s[8:9], vcc
	s_xor_b64 s[8:9], exec, s[8:9]
	s_cbranch_execz .LBB0_2698
	s_waitcnt lgkmcnt(0)
	v_mov_b32_e32 v1, 0
	global_load_dword v3, v1, s[6:7] sc1
	buffer_inv sc1
	s_waitcnt vmcnt(0)
	v_cmp_eq_u32_e32 vcc, v3, v2
	s_and_saveexec_b64 s[10:11], vcc
	s_cbranch_execz .LBB0_2697
	s_mov_b32 s24, 1
	s_mov_b64 s[12:13], 0
	s_branch .LBB0_2688

.LBB0_2778:
	s_or_b64 exec, exec, s[10:11]
	v_cvt_f32_u32_e32 v5, v3
	s_waitcnt vmcnt(0)
	v_readfirstlane_b32 s8, v4
	s_add_u32 s6, s6, 0x2400
	s_addc_u32 s7, s7, 0
	v_add_u32_e32 v6, s8, v2
	v_add_u32_e32 v4, 1, v6
	v_mul_u32_u24_e32 v3, 31, v3
	v_mov_b32_e32 v2, 30
	v_cmp_ne_u32_e32 vcc, v4, v3
	s_and_saveexec_b64 s[8:9], vcc
	s_xor_b64 s[8:9], exec, s[8:9]
	s_cbranch_execz .LBB0_2792
	s_waitcnt lgkmcnt(0)
	v_mov_b32_e32 v1, 0
	global_load_dword v3, v1, s[6:7] sc1
	buffer_inv sc1
	s_waitcnt vmcnt(0)
	v_cmp_eq_u32_e32 vcc, v3, v2
	s_and_saveexec_b64 s[10:11], vcc
	s_cbranch_execz .LBB0_2791
	s_mov_b32 s24, 1
	s_mov_b64 s[12:13], 0
	s_branch .LBB0_2782

.LBB0_2875:
	s_or_b64 exec, exec, s[10:11]
	v_cvt_f32_u32_e32 v5, v3
	s_waitcnt vmcnt(0)
	v_readfirstlane_b32 s8, v4
	s_add_u32 s6, s6, 0x2400
	s_addc_u32 s7, s7, 0
	v_add_u32_e32 v6, s8, v2
	v_add_u32_e32 v4, 1, v6
	v_mul_u32_u24_e32 v3, 32, v3
	v_mov_b32_e32 v2, 31
	v_cmp_ne_u32_e32 vcc, v4, v3
	s_and_saveexec_b64 s[8:9], vcc
	s_xor_b64 s[8:9], exec, s[8:9]
	s_cbranch_execz .LBB0_2889
	s_waitcnt lgkmcnt(0)
	v_mov_b32_e32 v1, 0
	global_load_dword v3, v1, s[6:7] sc1
	buffer_inv sc1
	s_waitcnt vmcnt(0)
	v_cmp_eq_u32_e32 vcc, v3, v2
	s_and_saveexec_b64 s[10:11], vcc
	s_cbranch_execz .LBB0_2888
	s_mov_b32 s24, 1
	s_mov_b64 s[12:13], 0
	s_branch .LBB0_2879

.LBB0_2947:
	s_or_b64 exec, exec, s[10:11]
	v_cvt_f32_u32_e32 v5, v3
	s_waitcnt vmcnt(0)
	v_readfirstlane_b32 s8, v4
	s_add_u32 s6, s6, 0x2400
	s_addc_u32 s7, s7, 0
	v_add_u32_e32 v6, s8, v2
	v_add_u32_e32 v4, 1, v6
	v_mul_u32_u24_e32 v3, 33, v3
	v_mov_b32_e32 v2, 32
	v_cmp_ne_u32_e32 vcc, v4, v3
	s_and_saveexec_b64 s[8:9], vcc
	s_xor_b64 s[8:9], exec, s[8:9]
	s_cbranch_execz .LBB0_2961
	s_waitcnt lgkmcnt(0)
	v_mov_b32_e32 v1, 0
	global_load_dword v3, v1, s[6:7] sc1
	buffer_inv sc1
	s_waitcnt vmcnt(0)
	v_cmp_eq_u32_e32 vcc, v3, v2
	s_and_saveexec_b64 s[10:11], vcc
	s_cbranch_execz .LBB0_2960
	s_mov_b32 s24, 1
	s_mov_b64 s[12:13], 0
	s_branch .LBB0_2951

.LBB0_3045:
	s_or_b64 exec, exec, s[10:11]
	v_cvt_f32_u32_e32 v5, v3
	s_waitcnt vmcnt(0)
	v_readfirstlane_b32 s8, v4
	s_add_u32 s6, s6, 0x2400
	s_addc_u32 s7, s7, 0
	v_add_u32_e32 v6, s8, v2
	v_add_u32_e32 v4, 1, v6
	v_mul_u32_u24_e32 v3, 34, v3
	v_mov_b32_e32 v2, 33
	v_cmp_ne_u32_e32 vcc, v4, v3
	s_and_saveexec_b64 s[8:9], vcc
	s_xor_b64 s[8:9], exec, s[8:9]
	s_cbranch_execz .LBB0_3059
	s_waitcnt lgkmcnt(0)
	v_mov_b32_e32 v1, 0
	global_load_dword v3, v1, s[6:7] sc1
	buffer_inv sc1
	s_waitcnt vmcnt(0)
	v_cmp_eq_u32_e32 vcc, v3, v2
	s_and_saveexec_b64 s[10:11], vcc
	s_cbranch_execz .LBB0_3058
	s_mov_b32 s24, 1
	s_mov_b64 s[12:13], 0
	s_branch .LBB0_3049

.LBB0_3108:
	s_or_b64 exec, exec, s[10:11]
	v_cvt_f32_u32_e32 v5, v3
	s_waitcnt vmcnt(0)
	v_readfirstlane_b32 s8, v4
	s_add_u32 s6, s6, 0x2400
	s_addc_u32 s7, s7, 0
	v_add_u32_e32 v6, s8, v2
	v_add_u32_e32 v4, 1, v6
	v_mul_u32_u24_e32 v3, 35, v3
	v_mov_b32_e32 v2, 34
	v_cmp_ne_u32_e32 vcc, v4, v3
	s_and_saveexec_b64 s[8:9], vcc
	s_xor_b64 s[8:9], exec, s[8:9]
	s_cbranch_execz .LBB0_3122
	s_waitcnt lgkmcnt(0)
	v_mov_b32_e32 v1, 0
	global_load_dword v3, v1, s[6:7] sc1
	buffer_inv sc1
	s_waitcnt vmcnt(0)
	v_cmp_eq_u32_e32 vcc, v3, v2
	s_and_saveexec_b64 s[10:11], vcc
	s_cbranch_execz .LBB0_3121
	s_mov_b32 s24, 1
	s_mov_b64 s[12:13], 0
	s_branch .LBB0_3112

.LBB0_3169:
	s_or_b64 exec, exec, s[10:11]
	v_cvt_f32_u32_e32 v5, v3
	s_waitcnt vmcnt(0)
	v_readfirstlane_b32 s8, v4
	s_add_u32 s6, s6, 0x2400
	s_addc_u32 s7, s7, 0
	v_add_u32_e32 v6, s8, v2
	v_add_u32_e32 v4, 1, v6
	v_mul_u32_u24_e32 v3, 36, v3
	v_mov_b32_e32 v2, 35
	v_cmp_ne_u32_e32 vcc, v4, v3
	s_and_saveexec_b64 s[8:9], vcc
	s_xor_b64 s[8:9], exec, s[8:9]
	s_cbranch_execz .LBB0_3183
	s_waitcnt lgkmcnt(0)
	v_mov_b32_e32 v1, 0
	global_load_dword v3, v1, s[6:7] sc1
	buffer_inv sc1
	s_waitcnt vmcnt(0)
	v_cmp_eq_u32_e32 vcc, v3, v2
	s_and_saveexec_b64 s[10:11], vcc
	s_cbranch_execz .LBB0_3182
	s_mov_b32 s22, 1
	s_mov_b64 s[12:13], 0
	s_branch .LBB0_3173

.LBB0_3250:
	s_or_b64 exec, exec, s[10:11]
	v_cvt_f32_u32_e32 v5, v3
	s_waitcnt vmcnt(0)
	v_readfirstlane_b32 s8, v4
	s_add_u32 s6, s6, 0x2400
	s_addc_u32 s7, s7, 0
	v_add_u32_e32 v6, s8, v2
	v_add_u32_e32 v4, 1, v6
	v_mul_u32_u24_e32 v3, 37, v3
	v_mov_b32_e32 v2, 36
	v_cmp_ne_u32_e32 vcc, v4, v3
	s_and_saveexec_b64 s[8:9], vcc
	s_xor_b64 s[8:9], exec, s[8:9]
	s_cbranch_execz .LBB0_3264
	s_waitcnt lgkmcnt(0)
	v_mov_b32_e32 v1, 0
	global_load_dword v3, v1, s[6:7] sc1
	buffer_inv sc1
	s_waitcnt vmcnt(0)
	v_cmp_eq_u32_e32 vcc, v3, v2
	s_and_saveexec_b64 s[10:11], vcc
	s_cbranch_execz .LBB0_3263
	s_mov_b32 s22, 1
	s_mov_b64 s[12:13], 0
	s_branch .LBB0_3254

.LBB0_3330:
	s_or_b64 exec, exec, s[10:11]
	v_cvt_f32_u32_e32 v5, v3
	s_waitcnt vmcnt(0)
	v_readfirstlane_b32 s8, v4
	s_add_u32 s6, s6, 0x2400
	s_addc_u32 s7, s7, 0
	v_add_u32_e32 v6, s8, v2
	v_add_u32_e32 v4, 1, v6
	v_mul_u32_u24_e32 v3, 38, v3
	v_mov_b32_e32 v2, 37
	v_cmp_ne_u32_e32 vcc, v4, v3
	s_and_saveexec_b64 s[8:9], vcc
	s_xor_b64 s[8:9], exec, s[8:9]
	s_cbranch_execz .LBB0_3344
	s_waitcnt lgkmcnt(0)
	v_mov_b32_e32 v1, 0
	global_load_dword v3, v1, s[6:7] sc1
	buffer_inv sc1
	s_waitcnt vmcnt(0)
	v_cmp_eq_u32_e32 vcc, v3, v2
	s_and_saveexec_b64 s[10:11], vcc
	s_cbranch_execz .LBB0_3343
	s_mov_b32 s22, 1
	s_mov_b64 s[12:13], 0
	s_branch .LBB0_3334

.LBB0_3424:
	s_or_b64 exec, exec, s[10:11]
	v_cvt_f32_u32_e32 v5, v3
	s_waitcnt vmcnt(0)
	v_readfirstlane_b32 s3, v4
	s_add_u32 s6, s6, 0x2400
	s_addc_u32 s7, s7, 0
	v_add_u32_e32 v6, s3, v2
	v_add_u32_e32 v4, 1, v6
	v_mul_u32_u24_e32 v3, 39, v3
	v_mov_b32_e32 v2, 38
	v_cmp_ne_u32_e32 vcc, v4, v3
	s_and_saveexec_b64 s[8:9], vcc
	s_xor_b64 s[8:9], exec, s[8:9]
	s_cbranch_execz .LBB0_3438
	s_waitcnt lgkmcnt(0)
	v_mov_b32_e32 v1, 0
	global_load_dword v3, v1, s[6:7] sc1
	buffer_inv sc1
	s_waitcnt vmcnt(0)
	v_cmp_eq_u32_e32 vcc, v3, v2
	s_and_saveexec_b64 s[10:11], vcc
	s_cbranch_execz .LBB0_3437
	s_mov_b32 s3, 1
	s_mov_b64 s[12:13], 0
	s_branch .LBB0_3428

.LBB0_3522:
	s_or_b64 exec, exec, s[8:9]
	v_cvt_f32_u32_e32 v5, v3
	s_waitcnt vmcnt(0)
	v_readfirstlane_b32 s6, v4
	s_add_u32 s4, s4, 0x2400
	s_addc_u32 s5, s5, 0
	v_add_u32_e32 v6, s6, v2
	v_add_u32_e32 v4, 1, v6
	v_mul_u32_u24_e32 v3, 40, v3
	v_mov_b32_e32 v2, 39
	v_cmp_ne_u32_e32 vcc, v4, v3
	s_and_saveexec_b64 s[6:7], vcc
	s_xor_b64 s[6:7], exec, s[6:7]
	s_cbranch_execz .LBB0_3536
	s_waitcnt lgkmcnt(0)
	v_mov_b32_e32 v1, 0
	global_load_dword v3, v1, s[4:5] sc1
	buffer_inv sc1
	s_waitcnt vmcnt(0)
	v_cmp_eq_u32_e32 vcc, v3, v2
	s_and_saveexec_b64 s[8:9], vcc
	s_cbranch_execz .LBB0_3535
	s_mov_b32 s20, 1
	s_mov_b64 s[10:11], 0
	s_branch .LBB0_3526

.LBB0_3592:
	s_or_b64 exec, exec, s[8:9]
	v_cvt_f32_u32_e32 v4, v2
	s_waitcnt vmcnt(0)
	v_readfirstlane_b32 s6, v3
	s_add_u32 s4, s4, 0x2400
	s_addc_u32 s5, s5, 0
	v_add_u32_e32 v5, s6, v1
	v_add_u32_e32 v3, 1, v5
	v_mul_u32_u24_e32 v2, 41, v2
	v_mov_b32_e32 v1, 40
	v_cmp_ne_u32_e32 vcc, v3, v2
	s_and_saveexec_b64 s[6:7], vcc
	s_xor_b64 s[6:7], exec, s[6:7]
	s_cbranch_execz .LBB0_3606
	s_waitcnt lgkmcnt(0)
	v_mov_b32_e32 v0, 0
	global_load_dword v2, v0, s[4:5] sc1
	buffer_inv sc1
	s_waitcnt vmcnt(0)
	v_cmp_eq_u32_e32 vcc, v2, v1
	s_and_saveexec_b64 s[8:9], vcc
	s_cbranch_execz .LBB0_3605
	s_mov_b32 s20, 1
	s_mov_b64 s[10:11], 0
	s_branch .LBB0_3596
